# grid-barrier polling loops: s_sleep 1 removed from the four poll loops (tighter release detection across the 20 phase barriers)
# baseline (speedup 1.0000x reference)
; __device__ __forceinline__ unsigned xb_ld(unsigned* p)              { return __hip_atomic_load(p, __ATOMIC_RELAXED, __HIP_MEMORY_SCOPE_AGENT); }
; __device__ __forceinline__ void xcd_barrier_complete(unsigned* bar, unsigned x, unsigned& nloc, unsigned& nx) {
;     ...
;     for (;;) {
;         sum = 0u; cnt = 0u; mine = 0u;
; #pragma unroll
;         for (unsigned j = 0; j < 16; ++j) { const unsigned c = xb_ld(&bar[XB_XCNT(j)]); sum += c; cnt += (c > 0u) ? 1u : 0u; mine = (j == x) ? c : mine; }
;         if (sum == G) break;
;         __builtin_amdgcn_s_sleep(1);
;         if ((++sp & 255u) == 0u) { if (xb_ld(&bar[XB_TMO])) break; if (sp > XB_SPIN_CAP) { atomicAdd(&bar[XB_TMO], 1u); break; } }
;     }
.LBB0_1067:
	v_readlane_b32 s26, v253, 21
	v_readlane_b32 s27, v253, 22
	v_readlane_b32 s3, v253, 6
	s_mov_b64 s[28:29], -1
	s_waitcnt lgkmcnt(0)
	s_nop 1
	global_load_dword v0, v209, s[26:27] sc1
	v_readlane_b32 s26, v253, 23
	v_readlane_b32 s27, v253, 24
	s_nop 4
	global_load_dword v1, v209, s[26:27] sc1
	v_readlane_b32 s26, v253, 25
	v_readlane_b32 s27, v253, 26
	s_waitcnt vmcnt(0)
	v_add_u32_e32 v16, v1, v0
	s_nop 2
	global_load_dword v2, v209, s[26:27] sc1
	v_readlane_b32 s26, v253, 27
	v_readlane_b32 s27, v253, 28
	s_waitcnt vmcnt(0)
	v_add_u32_e32 v16, v16, v2
	s_nop 2
	global_load_dword v3, v209, s[26:27] sc1
	v_readlane_b32 s26, v253, 29
	v_readlane_b32 s27, v253, 30
	s_waitcnt vmcnt(0)
	v_add_u32_e32 v16, v16, v3
	s_nop 2
	global_load_dword v4, v209, s[26:27] sc1
	v_readlane_b32 s26, v253, 31
	v_readlane_b32 s27, v253, 32
	s_waitcnt vmcnt(0)
	v_add_u32_e32 v16, v16, v4
	s_nop 2
	global_load_dword v5, v209, s[26:27] sc1
	v_readlane_b32 s26, v253, 33
	v_readlane_b32 s27, v253, 34
	s_waitcnt vmcnt(0)
	v_add_u32_e32 v16, v16, v5
	s_nop 2
	global_load_dword v6, v209, s[26:27] sc1
	v_readlane_b32 s26, v253, 35
	v_readlane_b32 s27, v253, 36
	s_waitcnt vmcnt(0)
	v_add_u32_e32 v16, v16, v6
	s_nop 2
	global_load_dword v7, v209, s[26:27] sc1
	v_readlane_b32 s26, v253, 37
	v_readlane_b32 s27, v253, 38
	s_waitcnt vmcnt(0)
	v_add_u32_e32 v16, v16, v7
	s_nop 2
	global_load_dword v8, v209, s[26:27] sc1
	v_readlane_b32 s26, v253, 39
	v_readlane_b32 s27, v253, 40
	s_waitcnt vmcnt(0)
	v_add_u32_e32 v16, v16, v8
	s_nop 2
	global_load_dword v9, v209, s[26:27] sc1
	v_readlane_b32 s26, v253, 41
	v_readlane_b32 s27, v253, 42
	s_waitcnt vmcnt(0)
	v_add_u32_e32 v16, v16, v9
	s_nop 2
	global_load_dword v10, v209, s[26:27] sc1
	v_readlane_b32 s26, v253, 43
	v_readlane_b32 s27, v253, 44
	s_waitcnt vmcnt(0)
	v_add_u32_e32 v16, v16, v10
	s_nop 2
	global_load_dword v11, v209, s[26:27] sc1
	v_readlane_b32 s26, v253, 45
	v_readlane_b32 s27, v253, 46
	s_waitcnt vmcnt(0)
	v_add_u32_e32 v16, v16, v11
	s_nop 2
	global_load_dword v12, v209, s[26:27] sc1
	v_readlane_b32 s26, v253, 47
	v_readlane_b32 s27, v253, 48
	s_waitcnt vmcnt(0)
	v_add_u32_e32 v16, v16, v12
	s_nop 2
	global_load_dword v13, v209, s[26:27] sc1
	v_readlane_b32 s26, v253, 49
	v_readlane_b32 s27, v253, 50
	s_waitcnt vmcnt(0)
	v_add_u32_e32 v16, v16, v13
	s_nop 2
	global_load_dword v14, v209, s[26:27] sc1
	v_readlane_b32 s26, v253, 51
	v_readlane_b32 s27, v253, 52
	s_waitcnt vmcnt(0)
	v_add_u32_e32 v16, v16, v14
	s_nop 2
	global_load_dword v15, v209, s[26:27] sc1
	s_mov_b64 s[26:27], -1
	s_waitcnt vmcnt(0)
	v_add_u32_e32 v16, v16, v15
	v_cmp_eq_u32_e32 vcc, s3, v16
	s_cbranch_vccnz .LBB0_1066
	s_and_b32 s3, s2, 0xff
	s_cmp_eq_u32 s3, 0
	s_mov_b64 s[36:37], -1
	s_cbranch_scc1 .LBB0_1071
	s_and_b64 vcc, exec, s[36:37]
	s_cbranch_vccz .LBB0_1066

.LBB0_1085:
	s_and_b32 s3, s2, 0xff
	s_mov_b64 s[40:41], -1
	s_cmp_lg_u32 s3, 0
	s_mov_b64 s[44:45], -1
	s_cbranch_scc0 .LBB0_1088
	s_and_b64 vcc, exec, s[44:45]
	s_cbranch_vccz .LBB0_1084

; __global__ void __launch_bounds__(NTHR) mega(Params p) {
;     ...
;         if (ph + 1 < p.ph_hi) { if (p.ph_hi < 0) grid.sync(); else xcd_barrier(xbar); }
.LBB0_1125:
	global_load_dword v1, v209, s[26:27] offset:32 sc1
	s_waitcnt vmcnt(0)
	v_and_b32_e32 v1, 0xffff0000, v1
	v_cmp_ne_u32_e32 vcc, v1, v0
	s_or_b64 s[28:29], vcc, s[28:29]
	s_andn2_b64 exec, exec, s[28:29]
	s_cbranch_execnz .LBB0_1125
	s_branch .LBB0_7
